# chain loop: one static s_setprio 1 for waves 4-7 (younger half) for the duration of the state-chain loop
# speedup vs baseline: 1.0057x; 1.0057x over previous
.LBB0_500:
	s_andn2_b64 vcc, exec, s[2:3]
	s_cbranch_vccnz .LBB0_505
	s_cmp_gt_u32 s20, 63
	s_cbranch_scc1 .LBB0_505
	s_lshr_b32 s4, s20, 3
	s_bfe_u32 s12, s20, 0x20001
	s_and_b32 s14, s20, 1
	s_bfe_i32 s5, s20, 0x10000
	s_lshl_b32 s15, s4, 2
	s_add_u32 s8, s22, 0x2cbc000
	s_addc_u32 s9, s23, 0
	s_lshl_b32 s2, s12, 2
	s_lshl_b32 s3, s14, 4
	s_or_b32 s2, s3, s2
	s_waitcnt vmcnt(0)
	v_mov_b32_e32 v0, s2
	global_load_dword v1, v0, s[54:55]
	s_mov_b32 s10, 0x3f2aaaab
	v_mov_b32_e32 v16, 0x3ecc95a3
	v_mov_b32_e32 v0, 0x3f317218
	s_mov_b32 s11, 0x3f317218
	s_mov_b32 s13, 0xff800000
	v_mov_b32_e32 v22, 0x7f800000
	v_mov_b32_e32 v23, 0x7fc00000
	v_mov_b32_e32 v24, 0xff800000
	s_mov_b32 s25, 0x33800000
	v_lshrrev_b32_e32 v84, 4, v160
	s_cmp_eq_u32 s14, 0
	v_xor_b32_e32 v25, 0x7f, v84
	s_cselect_b64 s[2:3], -1, 0
	s_lshl_b32 s16, s4, 19
	s_lshl_b32 s17, s14, 18
	s_and_b32 s5, s5, 0xf80
	s_or_b32 s26, s16, s17
	s_add_u32 s16, s8, s26
	s_addc_u32 s17, s9, 0
	s_lshl_b32 s24, s12, 8
	v_and_b32_e32 v99, 15, v160
	s_add_u32 s16, s16, s24
	v_mov_b32_e32 v97, 0
	v_lshlrev_b32_e32 v96, 4, v99
	s_addc_u32 s17, s17, 0
	v_lshlrev_b32_e32 v2, 11, v84
	v_mov_b32_e32 v3, v97
	v_lshl_add_u64 v[4:5], s[16:17], 0, v[96:97]
	v_lshl_add_u64 v[6:7], v[4:5], 0, v[2:3]
	global_load_dwordx4 v[32:35], v[6:7], off
	global_load_dwordx4 v[36:39], v[6:7], off offset:1024
	v_add_u32_e32 v118, 0, v96
	v_bfe_u32 v146, v160, 6, 2
	v_lshrrev_b32_e32 v147, 8, v160
	v_bfe_u32 v64, v160, 2, 2
	v_lshlrev_b32_e32 v148, 3, v84
	v_lshlrev_b32_e32 v149, 7, v147
	v_lshlrev_b32_e32 v151, 6, v146
	v_and_or_b32 v152, v148, 24, v64
	v_mov_b32_e32 v117, v97
	v_mul_u32_u24_e32 v123, 0x130, v84
	s_waitcnt vmcnt(0)
	v_mul_f32_e32 v1, 0x3fb8aa3b, v1
	v_exp_f32_e32 v26, v1
	s_nop 0
	v_sub_f32_e32 v1, 1.0, v26
	v_add_f32_e32 v10, -1.0, v1
	v_frexp_mant_f32_e32 v11, v1
	v_cvt_f64_f32_e32 v[8:9], v1
	v_sub_f32_e32 v12, v10, v1
	v_frexp_exp_i32_f64_e32 v8, v[8:9]
	v_cmp_gt_f32_e32 vcc, s10, v11
	v_sub_f32_e64 v10, -v26, v10
	v_add_f32_e32 v9, 1.0, v12
	v_subbrev_co_u32_e32 v8, vcc, 0, v8, vcc
	v_add_f32_e32 v9, v10, v9
	v_sub_u32_e32 v10, 0, v8
	v_ldexp_f32 v1, v1, v10
	v_ldexp_f32 v9, v9, v10
	v_add_f32_e32 v10, -1.0, v1
	v_add_f32_e32 v12, 1.0, v1
	v_add_f32_e32 v11, 1.0, v10
	v_add_f32_e32 v13, -1.0, v12
	v_sub_f32_e32 v11, v1, v11
	v_sub_f32_e32 v1, v1, v13
	v_add_f32_e32 v1, v9, v1
	v_add_f32_e32 v13, v9, v11
	v_add_f32_e32 v9, v12, v1
	v_rcp_f32_e32 v17, v9
	v_add_f32_e32 v11, v10, v13
	v_sub_f32_e32 v12, v9, v12
	v_sub_f32_e32 v1, v1, v12
	v_mul_f32_e32 v19, v11, v17
	v_mul_f32_e32 v12, v9, v19
	v_fma_f32 v14, v19, v9, -v12
	v_sub_f32_e32 v10, v11, v10
	v_fmac_f32_e32 v14, v19, v1
	v_sub_f32_e32 v18, v13, v10
	v_add_f32_e32 v10, v12, v14
	v_sub_f32_e32 v13, v11, v10
	v_mov_b32_e32 v15, v10
	v_pk_add_f32 v[10:11], v[10:11], v[12:13] neg_lo:[0,1] neg_hi:[0,1]
	v_cvt_f32_i32_e32 v8, v8
	v_pk_add_f32 v[10:11], v[10:11], v[14:15] neg_lo:[0,1] neg_hi:[0,1]
	v_cmp_neq_f32_e32 vcc, s13, v26
	v_add_f32_e32 v11, v18, v11
	v_add_f32_e32 v10, v10, v11
	v_add_f32_e32 v11, v13, v10
	v_mul_f32_e32 v15, v17, v11
	v_mul_f32_e32 v12, v9, v15
	v_fma_f32 v14, v15, v9, -v12
	v_sub_f32_e32 v13, v13, v11
	v_fmac_f32_e32 v14, v15, v1
	v_add_f32_e32 v18, v10, v13
	v_add_f32_e32 v20, v19, v15
	v_add_f32_e32 v10, v12, v14
	v_sub_f32_e32 v9, v20, v19
	v_sub_f32_e32 v13, v11, v10
	v_sub_f32_e32 v1, v15, v9
	v_mov_b32_e32 v15, v10
	v_pk_add_f32 v[10:11], v[10:11], v[12:13] neg_lo:[0,1] neg_hi:[0,1]
	s_nop 0
	v_pk_add_f32 v[10:11], v[10:11], v[14:15] neg_lo:[0,1] neg_hi:[0,1]
	s_nop 0
	v_add_f32_e32 v9, v18, v11
	v_add_f32_e32 v9, v10, v9
	v_add_f32_e32 v9, v13, v9
	v_mul_f32_e32 v9, v17, v9
	v_add_f32_e32 v1, v1, v9
	v_add_f32_e32 v9, v20, v1
	v_mul_f32_e32 v10, v9, v9
	v_sub_f32_e32 v12, v9, v20
	v_fmac_f32_e32 v16, 0x3e9b6dac, v10
	v_ldexp_f32 v11, v9, 1
	v_sub_f32_e32 v12, v1, v12
	v_mul_f32_e32 v9, v9, v10
	v_fmaak_f32 v1, v10, v16, 0x3f2aaada
	v_pk_mul_f32 v[0:1], v[8:9], v[0:1]
	v_ldexp_f32 v13, v12, 1
	v_fma_f32 v9, v8, s11, -v0
	v_fmamk_f32 v10, v8, 0xb102e308, v9
	v_pk_add_f32 v[8:9], v[0:1], v[10:11]
	v_mov_b32_e32 v12, v0
	v_sub_f32_e32 v16, v9, v11
	v_pk_add_f32 v[14:15], v[8:9], v[0:1] neg_lo:[0,1] neg_hi:[0,1]
	v_sub_f32_e32 v1, v1, v16
	v_add_f32_e32 v13, v13, v1
	v_pk_add_f32 v[18:19], v[8:9], v[12:13]
	v_mov_b32_e32 v11, v8
	v_mov_b32_e32 v15, v19
	v_pk_add_f32 v[20:21], v[10:11], v[14:15] neg_lo:[0,1] neg_hi:[0,1]
	v_pk_add_f32 v[10:11], v[10:11], v[14:15]
	v_mov_b32_e32 v0, v9
	v_mov_b32_e32 v17, v8
	v_pk_add_f32 v[8:9], v[10:11], v[8:9] op_sel:[1,0] op_sel_hi:[0,1] neg_lo:[0,1] neg_hi:[0,1]
	v_mov_b32_e32 v16, v13
	v_mov_b32_e32 v12, v19
	v_mov_b32_e32 v13, v11
	v_mov_b32_e32 v1, v8
	v_pk_add_f32 v[14:15], v[18:19], v[8:9] op_sel_hi:[1,0] neg_lo:[0,1] neg_hi:[0,1]
	v_pk_add_f32 v[0:1], v[12:13], v[0:1] neg_lo:[0,1] neg_hi:[0,1]
	v_mov_b32_e32 v14, v20
	v_pk_add_f32 v[0:1], v[16:17], v[0:1] neg_lo:[0,1] neg_hi:[0,1]
	v_mov_b32_e32 v21, v11
	v_pk_add_f32 v[8:9], v[14:15], v[0:1]
	v_cmp_lt_f32_e64 s[10:11], |v26|, s25
	v_pk_add_f32 v[12:13], v[8:9], v[8:9] op_sel:[0,1] op_sel_hi:[1,0]
	s_add_u32 s25, s22, 0x74bc000
	v_pk_add_f32 v[10:11], v[10:11], v[12:13] op_sel:[1,0] op_sel_hi:[0,1]
	v_mov_b32_e32 v9, v10
	v_mov_b32_e32 v1, v12
	v_pk_add_f32 v[12:13], v[8:9], v[20:21] neg_lo:[0,1] neg_hi:[0,1]
	s_addc_u32 s27, s23, 0
	v_sub_f32_e32 v8, v8, v12
	v_pk_add_f32 v[0:1], v[0:1], v[12:13] neg_lo:[0,1] neg_hi:[0,1]
	v_sub_f32_e32 v8, v20, v8
	v_add_f32_e32 v0, v0, v8
	v_add_f32_e32 v0, v0, v1
	v_add_f32_e32 v0, v10, v0
	v_cndmask_b32_e32 v0, v22, v0, vcc
	v_cmp_nlt_f32_e32 vcc, 1.0, v26
	v_sub_u32_e32 v1, 0x5f, v84
	s_xor_b32 s13, s26, 0x40000
	v_cndmask_b32_e32 v0, v23, v0, vcc
	v_cmp_neq_f32_e32 vcc, 1.0, v26
	s_add_u32 s8, s8, s13
	s_addc_u32 s9, s9, 0
	v_cndmask_b32_e32 v0, v24, v0, vcc
	v_cndmask_b32_e64 v8, v0, -v26, s[10:11]
	v_mul_f32_e32 v0, 0x43000000, v8
	v_mul_f32_e32 v0, 0x3fb8aa3b, v0
	v_exp_f32_e32 v98, v0
	v_cndmask_b32_e64 v0, v84, v25, s[2:3]
	v_cvt_f32_ubyte0_e32 v0, v0
	v_mul_f32_e32 v0, v8, v0
	v_mul_f32_e32 v0, 0x3fb8aa3b, v0
	v_exp_f32_e32 v100, v0
	v_add_u32_e32 v0, 32, v84
	v_cndmask_b32_e64 v0, v0, v1, s[2:3]
	v_cvt_f32_ubyte0_e32 v0, v0
	v_mul_f32_e32 v0, v8, v0
	v_mul_f32_e32 v0, 0x3fb8aa3b, v0
	v_exp_f32_e32 v102, v0
	v_or_b32_e32 v0, 64, v84
	v_xor_b32_e32 v1, 63, v84
	s_mov_b32 s10, 0x10000
	v_cndmask_b32_e64 v9, v0, v1, s[2:3]
	v_add_co_u32_e32 v0, vcc, s10, v6
	s_mov_b32 s11, 0x30000
	s_nop 0
	v_addc_co_u32_e32 v1, vcc, 0, v7, vcc
	global_load_dwordx4 v[40:43], v[0:1], off
	global_load_dwordx4 v[44:47], v[0:1], off offset:1024
	v_cvt_f32_ubyte0_e32 v0, v9
	v_sub_u32_e32 v1, 31, v84
	v_mul_f32_e32 v0, v8, v0
	v_cvt_f32_i32_e32 v1, v1
	v_mul_f32_e32 v0, 0x3fb8aa3b, v0
	v_exp_f32_e32 v104, v0
	v_add_u32_e32 v0, 0x60, v84
	v_cvt_f32_ubyte0_e32 v0, v0
	v_cndmask_b32_e64 v0, v0, v1, s[2:3]
	v_mul_f32_e32 v0, v0, v8
	v_mul_f32_e32 v0, 0x3fb8aa3b, v0
	v_exp_f32_e32 v106, v0
	v_or_b32_e32 v0, 0x20000, v2
	v_mov_b32_e32 v1, v97
	v_lshl_add_u64 v[4:5], v[4:5], 0, v[0:1]
	global_load_dwordx4 v[48:51], v[4:5], off
	global_load_dwordx4 v[52:55], v[4:5], off offset:1024
	v_add_co_u32_e32 v4, vcc, s11, v6
	s_add_u32 s8, s8, s24
	s_nop 0
	v_addc_co_u32_e32 v5, vcc, 0, v7, vcc
	global_load_dwordx4 v[56:59], v[4:5], off
	global_load_dwordx4 v[60:63], v[4:5], off offset:1024
	s_addc_u32 s9, s9, 0
	v_lshl_add_u64 v[4:5], s[8:9], 0, v[96:97]
	v_lshl_add_u64 v[2:3], v[4:5], 0, v[2:3]
	v_add_co_u32_e32 v6, vcc, s10, v2
	v_lshl_add_u64 v[0:1], v[4:5], 0, v[0:1]
	s_nop 0
	v_addc_co_u32_e32 v7, vcc, 0, v3, vcc
	global_load_dwordx4 v[28:31], v[2:3], off
	global_load_dwordx4 v[24:27], v[2:3], off offset:1024
	global_load_dwordx4 v[20:23], v[6:7], off
	global_load_dwordx4 v[16:19], v[6:7], off offset:1024
	global_load_dwordx4 v[12:15], v[0:1], off
	global_load_dwordx4 v[8:11], v[0:1], off offset:1024
	v_add_co_u32_e32 v0, vcc, s11, v2
	s_movk_i32 s8, 0x130
	s_nop 0
	v_addc_co_u32_e32 v1, vcc, 0, v3, vcc
	v_mad_u32_u24 v65, v84, s8, v118
	global_load_dwordx4 v[4:7], v[0:1], off
	s_nop 0
	global_load_dwordx4 v[0:3], v[0:1], off offset:1024
	ds_write_b128 v65, v[32:35]
	v_lshlrev_b32_e32 v32, 16, v36
	v_and_b32_e32 v33, 0xffff0000, v36
	v_mov_b32_e32 v101, v100
	v_lshlrev_b32_e32 v34, 16, v37
	v_and_b32_e32 v35, 0xffff0000, v37
	v_pk_mul_f32 v[32:33], v[100:101], v[32:33] op_sel_hi:[0,1]
	v_pk_mul_f32 v[34:35], v[100:101], v[34:35] op_sel_hi:[0,1]
	v_cvt_pk_bf16_f32 v32, v32, v33
	v_cvt_pk_bf16_f32 v33, v34, v35
	v_lshlrev_b32_e32 v34, 16, v38
	v_and_b32_e32 v35, 0xffff0000, v38
	v_lshlrev_b32_e32 v36, 16, v39
	v_and_b32_e32 v37, 0xffff0000, v39
	v_pk_mul_f32 v[34:35], v[100:101], v[34:35] op_sel_hi:[0,1]
	v_pk_mul_f32 v[36:37], v[100:101], v[36:37] op_sel_hi:[0,1]
	v_cvt_pk_bf16_f32 v34, v34, v35
	v_cvt_pk_bf16_f32 v35, v36, v37
	ds_write_b128 v65, v[32:35] offset:38912
	v_mov_b32_e32 v32, 0x2600
	v_mad_u32_u24 v32, v84, s8, v32
	v_add_u32_e32 v119, v118, v32
	v_mov_b32_e32 v103, v102
	v_mov_b32_e32 v105, v104
	v_mov_b32_e32 v107, v106
	s_lshl_b32 s16, s4, 12
	s_or_b32 s4, s5, s16
	s_mulk_i32 s4, 0x1c00
	s_add_u32 s4, s25, s4
	s_addc_u32 s5, s27, 0
	s_add_u32 s4, s4, s24
	s_addc_u32 s5, s5, 0
	s_mov_b64 s[10:11], 0xa8000
	s_mov_b32 s26, 1
	s_mov_b32 s13, 0
	s_waitcnt vmcnt(0)
	ds_write_b128 v119, v[40:43]
	v_lshlrev_b32_e32 v32, 16, v44
	v_and_b32_e32 v33, 0xffff0000, v44
	v_lshlrev_b32_e32 v34, 16, v45
	v_and_b32_e32 v35, 0xffff0000, v45
	v_pk_mul_f32 v[32:33], v[102:103], v[32:33] op_sel_hi:[0,1]
	v_pk_mul_f32 v[34:35], v[102:103], v[34:35] op_sel_hi:[0,1]
	v_cvt_pk_bf16_f32 v32, v32, v33
	v_cvt_pk_bf16_f32 v33, v34, v35
	v_lshlrev_b32_e32 v34, 16, v46
	v_and_b32_e32 v35, 0xffff0000, v46
	v_lshlrev_b32_e32 v36, 16, v47
	v_and_b32_e32 v37, 0xffff0000, v47
	v_pk_mul_f32 v[34:35], v[102:103], v[34:35] op_sel_hi:[0,1]
	v_pk_mul_f32 v[36:37], v[102:103], v[36:37] op_sel_hi:[0,1]
	v_cvt_pk_bf16_f32 v34, v34, v35
	v_cvt_pk_bf16_f32 v35, v36, v37
	ds_write_b128 v119, v[32:35] offset:38912
	ds_write_b128 v119, v[48:51] offset:9728
	v_lshlrev_b32_e32 v32, 16, v52
	v_and_b32_e32 v33, 0xffff0000, v52
	v_lshlrev_b32_e32 v34, 16, v53
	v_and_b32_e32 v35, 0xffff0000, v53
	v_pk_mul_f32 v[32:33], v[104:105], v[32:33] op_sel_hi:[0,1]
	v_pk_mul_f32 v[34:35], v[104:105], v[34:35] op_sel_hi:[0,1]
	v_cvt_pk_bf16_f32 v32, v32, v33
	v_cvt_pk_bf16_f32 v33, v34, v35
	v_lshlrev_b32_e32 v34, 16, v54
	v_and_b32_e32 v35, 0xffff0000, v54
	v_lshlrev_b32_e32 v36, 16, v55
	v_and_b32_e32 v37, 0xffff0000, v55
	v_pk_mul_f32 v[34:35], v[104:105], v[34:35] op_sel_hi:[0,1]
	v_pk_mul_f32 v[36:37], v[104:105], v[36:37] op_sel_hi:[0,1]
	v_cvt_pk_bf16_f32 v34, v34, v35
	v_cvt_pk_bf16_f32 v35, v36, v37
	ds_write_b128 v119, v[32:35] offset:48640
	ds_write_b128 v119, v[56:59] offset:19456
	v_lshlrev_b32_e32 v32, 16, v60
	v_and_b32_e32 v33, 0xffff0000, v60
	v_lshlrev_b32_e32 v34, 16, v61
	v_and_b32_e32 v35, 0xffff0000, v61
	v_pk_mul_f32 v[32:33], v[106:107], v[32:33] op_sel_hi:[0,1]
	v_pk_mul_f32 v[34:35], v[106:107], v[34:35] op_sel_hi:[0,1]
	v_cvt_pk_bf16_f32 v32, v32, v33
	v_cvt_pk_bf16_f32 v33, v34, v35
	v_lshlrev_b32_e32 v34, 16, v62
	v_and_b32_e32 v35, 0xffff0000, v62
	v_lshlrev_b32_e32 v36, 16, v63
	v_and_b32_e32 v37, 0xffff0000, v63
	v_pk_mul_f32 v[34:35], v[106:107], v[34:35] op_sel_hi:[0,1]
	v_pk_mul_f32 v[36:37], v[106:107], v[36:37] op_sel_hi:[0,1]
	v_cvt_pk_bf16_f32 v34, v34, v35
	v_cvt_pk_bf16_f32 v35, v36, v37
	v_lshlrev_b32_e32 v36, 3, v160
	v_and_b32_e32 v150, 24, v36
	ds_write_b128 v119, v[32:35] offset:58368
	v_add3_u32 v120, 0, v149, v150
	v_add3_u32 v121, 0, v151, v150
	s_waitcnt lgkmcnt(0)
	s_barrier
	v_mad_u32_u24 v85, v152, s8, v120
	v_mad_u32_u24 v90, v152, s8, v121
	ds_read_b64_tr_b16 v[38:39], v85 offset:1216
	ds_read_b64_tr_b16 v[36:37], v85
	ds_read_b64_tr_b16 v[40:41], v85 offset:32
	ds_read_b64_tr_b16 v[44:45], v85 offset:64
	ds_read_b64_tr_b16 v[48:49], v85 offset:96
	ds_read_b64_tr_b16 v[54:55], v90 offset:40128
	ds_read_b64_tr_b16 v[52:53], v90 offset:38912
	ds_read_b64_tr_b16 v[42:43], v85 offset:1248
	ds_read_b64_tr_b16 v[46:47], v85 offset:1280
	ds_read_b64_tr_b16 v[50:51], v85 offset:1312
	ds_read_b64_tr_b16 v[58:59], v90 offset:40160
	ds_read_b64_tr_b16 v[56:57], v90 offset:38944
	v_mul_f32_e32 v32, 0, v98
	v_mov_b32_e32 v33, v32
	v_mov_b32_e32 v34, v32
	v_mov_b32_e32 v35, v32
	s_waitcnt lgkmcnt(0)
	s_nop 0
	v_mfma_f32_16x16x32_bf16 v[60:63], v[36:39], v[52:55], v[32:35]
	v_mfma_f32_16x16x32_bf16 v[36:39], v[36:39], v[56:59], v[32:35]
	v_mfma_f32_16x16x32_bf16 v[64:67], v[40:43], v[52:55], v[32:35]
	v_mfma_f32_16x16x32_bf16 v[40:43], v[40:43], v[56:59], v[32:35]
	v_mfma_f32_16x16x32_bf16 v[68:71], v[44:47], v[52:55], v[32:35]
	v_mfma_f32_16x16x32_bf16 v[44:47], v[44:47], v[56:59], v[32:35]
	v_mfma_f32_16x16x32_bf16 v[52:55], v[48:51], v[52:55], v[32:35]
	v_mfma_f32_16x16x32_bf16 v[32:35], v[48:51], v[56:59], v[32:35]
	ds_read_b64_tr_b16 v[50:51], v85 offset:10944
	ds_read_b64_tr_b16 v[48:49], v85 offset:9728
	ds_read_b64_tr_b16 v[56:57], v85 offset:9760
	ds_read_b64_tr_b16 v[72:73], v85 offset:9792
	ds_read_b64_tr_b16 v[76:77], v85 offset:9824
	ds_read_b64_tr_b16 v[80:81], v90 offset:48640
	ds_read_b64_tr_b16 v[82:83], v90 offset:49856
	ds_read_b64_tr_b16 v[58:59], v85 offset:10976
	ds_read_b64_tr_b16 v[74:75], v85 offset:11008
	ds_read_b64_tr_b16 v[78:79], v85 offset:11040
	ds_read_b64_tr_b16 v[88:89], v90 offset:49888
	ds_read_b64_tr_b16 v[86:87], v90 offset:48672
	s_waitcnt lgkmcnt(5)
	v_mfma_f32_16x16x32_bf16 v[60:63], v[48:51], v[80:83], v[60:63]
	s_waitcnt lgkmcnt(0)
	v_mfma_f32_16x16x32_bf16 v[36:39], v[48:51], v[86:89], v[36:39]
	v_mfma_f32_16x16x32_bf16 v[48:51], v[56:59], v[80:83], v[64:67]
	v_mfma_f32_16x16x32_bf16 v[40:43], v[56:59], v[86:89], v[40:43]
	v_mfma_f32_16x16x32_bf16 v[56:59], v[72:75], v[80:83], v[68:71]
	v_mfma_f32_16x16x32_bf16 v[44:47], v[72:75], v[86:89], v[44:47]
	v_mfma_f32_16x16x32_bf16 v[64:67], v[76:79], v[80:83], v[52:55]
	v_mfma_f32_16x16x32_bf16 v[68:71], v[76:79], v[86:89], v[32:35]
	s_nop 2
	ds_read_b64_tr_b16 v[34:35], v85 offset:20672
	ds_read_b64_tr_b16 v[32:33], v85 offset:19456
	ds_read_b64_tr_b16 v[52:53], v85 offset:19488
	ds_read_b64_tr_b16 v[72:73], v85 offset:19520
	ds_read_b64_tr_b16 v[76:77], v85 offset:19552
	ds_read_b64_tr_b16 v[80:81], v90 offset:58368
	ds_read_b64_tr_b16 v[82:83], v90 offset:59584
	ds_read_b64_tr_b16 v[54:55], v85 offset:20704
	ds_read_b64_tr_b16 v[74:75], v85 offset:20736
	ds_read_b64_tr_b16 v[78:79], v85 offset:20768
	ds_read_b64_tr_b16 v[88:89], v90 offset:59616
	ds_read_b64_tr_b16 v[86:87], v90 offset:58400
	s_waitcnt lgkmcnt(5)
	v_mfma_f32_16x16x32_bf16 v[60:63], v[32:35], v[80:83], v[60:63]
	s_waitcnt lgkmcnt(0)
	v_mfma_f32_16x16x32_bf16 v[36:39], v[32:35], v[86:89], v[36:39]
	v_mul_u32_u24_e32 v34, 0xe00, v84
	v_lshl_add_u64 v[32:33], s[4:5], 0, v[96:97]
	v_lshlrev_b32_e32 v116, 1, v34
	v_mfma_f32_16x16x32_bf16 v[108:111], v[52:55], v[86:89], v[40:43]
	v_lshl_add_u64 v[144:145], v[32:33], 0, v[116:117]
	s_mov_b64 s[4:5], 0x38000
	s_nop 0
	v_mov_b32_e32 v40, 0x7200
	v_mad_u32_u24 v40, v152, s8, v40
	v_mfma_f32_16x16x32_bf16 v[48:51], v[52:55], v[80:83], v[48:51]
	global_load_dwordx4 v[202:205], v[144:145], off offset:1024
	global_load_dwordx4 v[206:209], v[144:145], off offset:2048
	v_add_u32_e32 v122, v121, v40
	s_mov_b64 s[8:9], 0x70000
	v_mfma_f32_16x16x32_bf16 v[112:115], v[72:75], v[80:83], v[56:59]
	v_mfma_f32_16x16x32_bf16 v[124:127], v[72:75], v[86:89], v[44:47]
	s_nop 1
	v_lshl_add_u64 v[56:57], v[144:145], 0, s[4:5]
	v_mfma_f32_16x16x32_bf16 v[128:131], v[76:79], v[80:83], v[64:67]
	ds_read_b64_tr_b16 v[42:43], v85 offset:30400
	ds_read_b64_tr_b16 v[40:41], v85 offset:29184
	ds_read_b64_tr_b16 v[44:45], v85 offset:29216
	ds_read_b64_tr_b16 v[80:81], v85 offset:29248
	ds_read_b64_tr_b16 v[132:133], v85 offset:29280
	ds_read_b64_tr_b16 v[138:139], v122 offset:40128
	ds_read_b64_tr_b16 v[136:137], v122 offset:38912
	ds_read_b64_tr_b16 v[46:47], v85 offset:30432
	ds_read_b64_tr_b16 v[82:83], v85 offset:30464
	ds_read_b64_tr_b16 v[134:135], v85 offset:30496
	ds_read_b64_tr_b16 v[142:143], v122 offset:40160
	ds_read_b64_tr_b16 v[140:141], v122 offset:38944
	v_mfma_f32_16x16x32_bf16 v[88:91], v[76:79], v[86:89], v[68:71]
	s_waitcnt lgkmcnt(4)
	v_mfma_f32_16x16x32_bf16 v[68:71], v[44:47], v[136:139], v[48:51]
	s_nop 2
	v_lshl_add_u64 v[48:49], v[144:145], 0, s[8:9]
	v_mfma_f32_16x16x32_bf16 v[92:95], v[40:43], v[136:139], v[60:63]
	s_waitcnt lgkmcnt(0)
	v_mfma_f32_16x16x32_bf16 v[64:67], v[40:43], v[140:143], v[36:39]
	s_nop 2
	global_load_dwordx4 v[210:213], v[56:57], off offset:1024
	global_load_dwordx4 v[214:217], v[56:57], off offset:2048
	global_load_dwordx4 v[218:221], v[48:49], off offset:1024
	s_nop 0
	global_load_dwordx4 v[222:225], v[48:49], off offset:2048
	v_lshl_add_u64 v[48:49], v[144:145], 0, s[10:11]
	v_mfma_f32_16x16x32_bf16 v[72:75], v[44:47], v[140:143], v[108:111]
	global_load_dwordx4 v[226:229], v[48:49], off offset:1024
	s_nop 0
	global_load_dwordx4 v[230:233], v[48:49], off offset:2048
	v_mov_b32_e32 v108, v98
	v_mov_b32_e32 v109, v98
	v_mfma_f32_16x16x32_bf16 v[76:79], v[80:83], v[136:139], v[112:115]
	v_mfma_f32_16x16x32_bf16 v[80:83], v[80:83], v[140:143], v[124:127]
	v_mfma_f32_16x16x32_bf16 v[84:87], v[132:135], v[136:139], v[128:131]
	s_nop 1
	v_mul_u32_u24_e32 v124, 0x130, v152
	v_mfma_f32_16x16x32_bf16 v[88:91], v[132:135], v[140:143], v[88:91]
	s_lshl_b32 s14, s14, 5
	v_and_or_b32 v99, v148, 16, v99
	s_or_b32 s14, s15, s14
	v_lshlrev_b32_e32 v110, 4, v99
	v_mov_b32_e32 v111, v97
	v_lshrrev_b32_e32 v99, 1, v160
	s_add_i32 s17, 0, 0x13000
	s_or_b32 s12, s14, s12
	v_lshl_add_u64 v[110:111], s[22:23], 0, v[110:111]
	v_and_b32_e32 v112, 8, v99
	v_mov_b32_e32 v113, v97
	v_add_u32_e32 v115, s17, v96
	s_add_i32 s28, 0, 0x1c800
	v_add3_u32 v127, s17, v149, v150
	s_lshl_b32 s17, s12, 5
	v_lshl_add_u64 v[110:111], v[110:111], 0, v[112:113]
	s_mov_b64 s[14:15], 0x154bc000
	v_lshl_add_u64 v[110:111], v[110:111], 0, s[14:15]
	v_lshlrev_b32_e32 v99, 10, v147
	s_add_u32 s14, s25, s24
	v_lshl_or_b32 v114, v146, 12, v99
	s_addc_u32 s15, s27, 0
	v_add_u32_e32 v126, s28, v96
	v_add3_u32 v128, s28, v151, v150
	v_add_u32_e32 v130, 0x900, v114
	v_add_u32_e32 v132, 0xb00, v114
	v_lshl_add_u64 v[112:113], s[14:15], 0, v[96:97]
	v_lshl_add_u64 v[112:113], v[112:113], 0, v[116:117]
	s_mov_b32 s24, 30
	v_add_u32_e32 v125, v115, v123
	v_add_u32_e32 v126, v126, v123
	v_add_u32_e32 v127, v127, v124
	v_add_u32_e32 v128, v128, v124
	v_lshlrev_b32_e32 v96, 1, v114
	s_movk_i32 s25, 0x1000
	v_lshlrev_b32_e32 v114, 1, v130
	v_lshlrev_b32_e32 v116, 1, v132
	v_mov_b32_e32 v129, 0x1c00
	v_readfirstlane_b32 s98, v160
	s_nop 3
	s_lshr_b32 s98, s98, 8
	s_cmp_eq_u32 s98, 0
	s_cbranch_scc1 .Lchain_prio_done
	s_setprio 1
.Lchain_prio_done:
	v_lshlrev_b32_e32 v242, 16, v24
	v_and_b32_e32 v243, 0xffff0000, v24
	v_lshlrev_b32_e32 v244, 16, v25
	v_and_b32_e32 v245, 0xffff0000, v25
	v_lshlrev_b32_e32 v246, 16, v26
	v_and_b32_e32 v247, 0xffff0000, v26
	v_lshlrev_b32_e32 v248, 16, v27
	v_and_b32_e32 v249, 0xffff0000, v27
	v_pk_mul_f32 v[242:243], v[100:101], v[242:243]
	v_pk_mul_f32 v[244:245], v[100:101], v[244:245]
	v_pk_mul_f32 v[246:247], v[100:101], v[246:247]
	v_pk_mul_f32 v[248:249], v[100:101], v[248:249]
	v_cvt_pk_bf16_f32 v24, v242, v243
	v_cvt_pk_bf16_f32 v25, v244, v245
	v_cvt_pk_bf16_f32 v26, v246, v247
	v_cvt_pk_bf16_f32 v27, v248, v249
	ds_write_b128 v125, v[28:31]
	ds_write_b128 v126, v[24:27]
	v_lshlrev_b32_e32 v242, 16, v16
	v_and_b32_e32 v243, 0xffff0000, v16
	v_lshlrev_b32_e32 v244, 16, v17
	v_and_b32_e32 v245, 0xffff0000, v17
	v_lshlrev_b32_e32 v246, 16, v18
	v_and_b32_e32 v247, 0xffff0000, v18
	v_lshlrev_b32_e32 v248, 16, v19
	v_and_b32_e32 v249, 0xffff0000, v19
	v_pk_mul_f32 v[242:243], v[102:103], v[242:243]
	v_pk_mul_f32 v[244:245], v[102:103], v[244:245]
	v_pk_mul_f32 v[246:247], v[102:103], v[246:247]
	v_pk_mul_f32 v[248:249], v[102:103], v[248:249]
	v_cvt_pk_bf16_f32 v16, v242, v243
	v_cvt_pk_bf16_f32 v17, v244, v245
	v_cvt_pk_bf16_f32 v18, v246, v247
	v_cvt_pk_bf16_f32 v19, v248, v249
	ds_write_b128 v125, v[20:23] offset:9728
	ds_write_b128 v126, v[16:19] offset:9728
	v_lshlrev_b32_e32 v242, 16, v8
	v_and_b32_e32 v243, 0xffff0000, v8
	v_lshlrev_b32_e32 v244, 16, v9
	v_and_b32_e32 v245, 0xffff0000, v9
	v_lshlrev_b32_e32 v246, 16, v10
	v_and_b32_e32 v247, 0xffff0000, v10
	v_lshlrev_b32_e32 v248, 16, v11
	v_and_b32_e32 v249, 0xffff0000, v11
	v_pk_mul_f32 v[242:243], v[104:105], v[242:243]
	v_pk_mul_f32 v[244:245], v[104:105], v[244:245]
	v_pk_mul_f32 v[246:247], v[104:105], v[246:247]
	v_pk_mul_f32 v[248:249], v[104:105], v[248:249]
	v_cvt_pk_bf16_f32 v8, v242, v243
	v_cvt_pk_bf16_f32 v9, v244, v245
	v_cvt_pk_bf16_f32 v10, v246, v247
	v_cvt_pk_bf16_f32 v11, v248, v249
	ds_write_b128 v125, v[12:15] offset:19456
	ds_write_b128 v126, v[8:11] offset:19456
	v_lshlrev_b32_e32 v242, 16, v0
	v_and_b32_e32 v243, 0xffff0000, v0
	v_lshlrev_b32_e32 v244, 16, v1
	v_and_b32_e32 v245, 0xffff0000, v1
	v_lshlrev_b32_e32 v246, 16, v2
	v_and_b32_e32 v247, 0xffff0000, v2
	v_lshlrev_b32_e32 v248, 16, v3
	v_and_b32_e32 v249, 0xffff0000, v3
	v_pk_mul_f32 v[242:243], v[106:107], v[242:243]
	v_pk_mul_f32 v[244:245], v[106:107], v[244:245]
	v_pk_mul_f32 v[246:247], v[106:107], v[246:247]
	v_pk_mul_f32 v[248:249], v[106:107], v[248:249]
	v_cvt_pk_bf16_f32 v0, v242, v243
	v_cvt_pk_bf16_f32 v1, v244, v245
	v_cvt_pk_bf16_f32 v2, v246, v247
	v_cvt_pk_bf16_f32 v3, v248, v249
	ds_write_b128 v125, v[4:7] offset:29184
	ds_write_b128 v126, v[0:3] offset:29184
	s_waitcnt vmcnt(0)
.LBB0_503:
	v_mul_f32_e32 v0, v108, v92
	v_mul_f32_e32 v1, v109, v93
	v_mul_f32_e32 v4, v108, v64
	v_mul_f32_e32 v5, v109, v65
	v_mul_f32_e32 v8, v108, v68
	v_mul_f32_e32 v9, v109, v69
	v_mov_b32_e32 v99, v98
	s_waitcnt lgkmcnt(0)
	s_barrier
	s_add_i32 s27, s26, 2
	s_cmp_lt_u32 s26, 31
	s_cselect_b64 s[14:15], -1, 0
	s_and_b64 s[28:29], s[14:15], exec
	s_cselect_b32 s12, s27, 32
	s_add_i32 s30, s12, -2
	s_sub_i32 s12, 33, s12
	s_and_b64 s[28:29], s[2:3], exec
	s_cselect_b32 s12, s30, s12
	s_lshl_b32 s12, s12, 7
	s_add_i32 s12, s12, s16
	v_mad_i64_i32 v[234:235], s[28:29], s12, v129, v[112:113]
	v_lshl_add_u64 v[236:237], v[234:235], 0, s[4:5]
	v_lshl_add_u64 v[238:239], v[234:235], 0, s[8:9]
	v_lshl_add_u64 v[252:253], v[234:235], 0, s[10:11]
	global_load_dwordx4 v[170:173], v[234:235], off offset:1024
	global_load_dwordx4 v[174:177], v[234:235], off offset:2048
	global_load_dwordx4 v[178:181], v[236:237], off offset:1024
	global_load_dwordx4 v[182:185], v[236:237], off offset:2048
	global_load_dwordx4 v[186:189], v[238:239], off offset:1024
	global_load_dwordx4 v[190:193], v[238:239], off offset:2048
	global_load_dwordx4 v[194:197], v[252:253], off offset:1024
	global_load_dwordx4 v[198:201], v[252:253], off offset:2048
	v_mul_f32_e32 v2, v98, v94
	v_mul_f32_e32 v3, v99, v95
	ds_read_b64_tr_b16 v[12:13], v127 offset:1216
	ds_read_b64_tr_b16 v[10:11], v127
	ds_read_b64_tr_b16 v[14:15], v127 offset:32
	ds_read_b64_tr_b16 v[18:19], v127 offset:64
	ds_read_b64_tr_b16 v[22:23], v127 offset:96
	ds_read_b64_tr_b16 v[28:29], v128 offset:1216
	ds_read_b64_tr_b16 v[26:27], v128
	ds_read_b64_tr_b16 v[16:17], v127 offset:1248
	ds_read_b64_tr_b16 v[20:21], v127 offset:1280
	ds_read_b64_tr_b16 v[24:25], v127 offset:1312
	ds_read_b64_tr_b16 v[94:95], v128 offset:1248
	ds_read_b64_tr_b16 v[92:93], v128 offset:32
	v_mul_f32_e32 v6, v98, v66
	v_mul_f32_e32 v7, v99, v67
	s_waitcnt lgkmcnt(5)
	v_mfma_f32_16x16x32_bf16 v[0:3], v[10:13], v[26:29], v[0:3]
	v_mul_f32_e64 v64, v108, v72
	v_mul_f32_e64 v65, v109, v73
	v_mul_f32_e32 v66, v98, v74
	v_mul_f32_e32 v67, v99, v75
	v_mul_f32_e32 v68, v108, v76
	v_mul_f32_e32 v69, v109, v77
	s_waitcnt lgkmcnt(0)
	v_mfma_f32_16x16x32_bf16 v[4:7], v[10:13], v[92:95], v[4:7]
	v_mul_f32_e64 v10, v98, v70
	v_mul_f32_e64 v11, v99, v71
	v_mul_f32_e32 v12, v108, v80
	v_mul_f32_e32 v13, v109, v81
	v_mul_f32_e32 v72, v108, v84
	v_mul_f32_e32 v73, v109, v85
	v_mfma_f32_16x16x32_bf16 v[8:11], v[14:17], v[26:29], v[8:11]
	v_mul_f32_e64 v76, v108, v88
	v_mul_f32_e64 v77, v109, v89
	v_mul_f32_e32 v70, v98, v78
	v_mul_f32_e32 v71, v99, v79
	v_mul_f32_e32 v74, v98, v86
	v_mul_f32_e32 v75, v99, v87
	v_mfma_f32_16x16x32_bf16 v[64:67], v[14:17], v[92:95], v[64:67]
	v_mul_f32_e64 v14, v98, v82
	v_mul_f32_e64 v15, v99, v83
	v_mul_f32_e32 v78, v98, v90
	v_mul_f32_e32 v79, v99, v91
	ds_read_b64_tr_b16 v[16:17], v127 offset:9728
	ds_read_b64_tr_b16 v[80:81], v127 offset:9760
	ds_read_b64_tr_b16 v[84:85], v127 offset:9792
	v_mfma_f32_16x16x32_bf16 v[68:71], v[18:21], v[26:29], v[68:71]
	s_nop 2
	v_mfma_f32_16x16x32_bf16 v[12:15], v[18:21], v[92:95], v[12:15]
	ds_read_b64_tr_b16 v[18:19], v127 offset:10944
	ds_read_b64_tr_b16 v[82:83], v127 offset:10976
	ds_read_b64_tr_b16 v[86:87], v127 offset:11008
	s_nop 1
	v_mfma_f32_16x16x32_bf16 v[26:29], v[22:25], v[26:29], v[72:75]
	ds_read_b64_tr_b16 v[20:21], v127 offset:9824
	s_nop 1
	ds_read_b64_tr_b16 v[72:73], v128 offset:9728
	ds_read_b64_tr_b16 v[74:75], v128 offset:10944
	s_nop 1
	v_mfma_f32_16x16x32_bf16 v[76:79], v[22:25], v[92:95], v[76:79]
	ds_read_b64_tr_b16 v[22:23], v127 offset:11040
	ds_read_b64_tr_b16 v[90:91], v128 offset:10976
	ds_read_b64_tr_b16 v[88:89], v128 offset:9760
	s_nop 1
	s_waitcnt lgkmcnt(3)
	v_mfma_f32_16x16x32_bf16 v[0:3], v[16:19], v[72:75], v[0:3]
	s_nop 1
	s_add_i32 s30, s24, 1
	s_waitcnt lgkmcnt(0)
	v_mfma_f32_16x16x32_bf16 v[4:7], v[16:19], v[88:91], v[4:7]
	v_mov_b32_e32 v115, v97
	v_mov_b32_e32 v117, v97
	v_mfma_f32_16x16x32_bf16 v[16:19], v[80:83], v[88:91], v[64:67]
	s_nop 2
	ds_read_b64_tr_b16 v[64:65], v127 offset:19456
	v_mfma_f32_16x16x32_bf16 v[8:11], v[80:83], v[72:75], v[8:11]
	ds_read_b64_tr_b16 v[66:67], v127 offset:20672
	ds_read_b64_tr_b16 v[82:83], v127 offset:20704
	ds_read_b64_tr_b16 v[94:95], v127 offset:20736
	v_mfma_f32_16x16x32_bf16 v[68:71], v[84:87], v[72:75], v[68:71]
	v_mfma_f32_16x16x32_bf16 v[12:15], v[84:87], v[88:91], v[12:15]
	ds_read_b64_tr_b16 v[80:81], v127 offset:19488
	ds_read_b64_tr_b16 v[92:93], v127 offset:19520
	ds_read_b64_tr_b16 v[84:85], v127 offset:19552
	v_mfma_f32_16x16x32_bf16 v[24:27], v[20:23], v[72:75], v[26:29]
	ds_read_b64_tr_b16 v[86:87], v127 offset:20768
	ds_read_b64_tr_b16 v[72:73], v128 offset:19456
	ds_read_b64_tr_b16 v[74:75], v128 offset:20672
	v_mfma_f32_16x16x32_bf16 v[20:23], v[20:23], v[88:91], v[76:79]
	s_nop 2
	ds_read_b64_tr_b16 v[78:79], v128 offset:20704
	ds_read_b64_tr_b16 v[76:77], v128 offset:19488
	ds_read_b64_tr_b16 v[88:89], v127 offset:29184
	ds_read_b64_tr_b16 v[90:91], v127 offset:30400
	ds_read_b64_tr_b16 v[132:133], v127 offset:30432
	ds_read_b64_tr_b16 v[136:137], v127 offset:30464
	ds_read_b64_tr_b16 v[130:131], v127 offset:29216
	ds_read_b64_tr_b16 v[134:135], v127 offset:29248
	ds_read_b64_tr_b16 v[138:139], v127 offset:29280
	ds_read_b64_tr_b16 v[140:141], v127 offset:30496
	ds_read_b64_tr_b16 v[146:147], v128 offset:29184
	ds_read_b64_tr_b16 v[148:149], v128 offset:30400
	s_waitcnt vmcnt(22)
	v_add_u32_e32 v250, v118, v123
	v_lshlrev_b32_e32 v242, 16, v206
	v_and_b32_e32 v243, 0xffff0000, v206
	v_lshlrev_b32_e32 v244, 16, v207
	v_and_b32_e32 v245, 0xffff0000, v207
	v_lshlrev_b32_e32 v246, 16, v208
	v_and_b32_e32 v247, 0xffff0000, v208
	v_lshlrev_b32_e32 v248, 16, v209
	v_and_b32_e32 v249, 0xffff0000, v209
	v_mul_f32_e32 v242, v100, v242
	v_mul_f32_e32 v243, v101, v243
	v_mul_f32_e32 v244, v100, v244
	v_mul_f32_e32 v245, v101, v245
	v_mul_f32_e32 v246, v100, v246
	v_mul_f32_e32 v247, v101, v247
	v_mul_f32_e32 v248, v100, v248
	v_mul_f32_e32 v249, v101, v249
	v_cvt_pk_bf16_f32 v206, v242, v243
	v_cvt_pk_bf16_f32 v207, v244, v245
	v_cvt_pk_bf16_f32 v208, v246, v247
	v_cvt_pk_bf16_f32 v209, v248, v249
	ds_write_b128 v250, v[202:205]
	ds_write_b128 v250, v[206:209] offset:38912
	s_waitcnt lgkmcnt(14)
	v_mfma_f32_16x16x32_bf16 v[0:3], v[64:67], v[72:75], v[0:3]
	ds_read_b64_tr_b16 v[152:153], v128 offset:30432
	ds_read_b64_tr_b16 v[150:151], v128 offset:29216
	s_waitcnt vmcnt(20)
	v_lshlrev_b32_e32 v242, 16, v214
	v_and_b32_e32 v243, 0xffff0000, v214
	v_lshlrev_b32_e32 v244, 16, v215
	v_and_b32_e32 v245, 0xffff0000, v215
	v_lshlrev_b32_e32 v246, 16, v216
	v_and_b32_e32 v247, 0xffff0000, v216
	v_lshlrev_b32_e32 v248, 16, v217
	v_and_b32_e32 v249, 0xffff0000, v217
	v_mul_f32_e32 v242, v102, v242
	v_mul_f32_e32 v243, v103, v243
	v_mul_f32_e32 v244, v102, v244
	v_mul_f32_e32 v245, v103, v245
	v_mul_f32_e32 v246, v102, v246
	v_mul_f32_e32 v247, v103, v247
	v_mul_f32_e32 v248, v102, v248
	v_mul_f32_e32 v249, v103, v249
	v_cvt_pk_bf16_f32 v214, v242, v243
	v_cvt_pk_bf16_f32 v215, v244, v245
	v_cvt_pk_bf16_f32 v216, v246, v247
	v_cvt_pk_bf16_f32 v217, v248, v249
	ds_write_b128 v250, v[210:213] offset:9728
	ds_write_b128 v250, v[214:217] offset:48640
	s_waitcnt lgkmcnt(15)
	v_mfma_f32_16x16x32_bf16 v[64:67], v[64:67], v[76:79], v[4:7]
	s_nop 2
	v_mfma_f32_16x16x32_bf16 v[142:145], v[80:83], v[72:75], v[8:11]
	s_add_i32 s12, s26, -1
	v_mfma_f32_16x16x32_bf16 v[80:83], v[80:83], v[76:79], v[16:19]
	s_and_b64 s[28:29], s[2:3], exec
	s_cselect_b32 s12, s12, s30
	s_add_i32 s12, s12, s17
	v_mfma_f32_16x16x32_bf16 v[154:157], v[92:95], v[72:75], v[68:71]
	s_lshl_b64 s[28:29], s[12:13], 15
	v_mfma_f32_16x16x32_bf16 v[162:165], v[92:95], v[76:79], v[12:15]
	s_nop 0
	v_mfma_f32_16x16x32_bf16 v[166:169], v[84:87], v[72:75], v[24:27]
	s_nop 2
	v_mfma_f32_16x16x32_bf16 v[84:87], v[84:87], v[76:79], v[20:23]
	s_nop 2
	s_nop 0
	s_nop 0
	s_waitcnt vmcnt(18)
	v_lshlrev_b32_e32 v242, 16, v222
	v_and_b32_e32 v243, 0xffff0000, v222
	v_lshlrev_b32_e32 v244, 16, v223
	v_and_b32_e32 v245, 0xffff0000, v223
	v_lshlrev_b32_e32 v246, 16, v224
	v_and_b32_e32 v247, 0xffff0000, v224
	v_lshlrev_b32_e32 v248, 16, v225
	v_and_b32_e32 v249, 0xffff0000, v225
	v_mul_f32_e32 v242, v104, v242
	v_mul_f32_e32 v243, v105, v243
	v_mul_f32_e32 v244, v104, v244
	v_mul_f32_e32 v245, v105, v245
	v_mul_f32_e32 v246, v104, v246
	v_mul_f32_e32 v247, v105, v247
	v_mul_f32_e32 v248, v104, v248
	v_mul_f32_e32 v249, v105, v249
	v_cvt_pk_bf16_f32 v222, v242, v243
	v_cvt_pk_bf16_f32 v223, v244, v245
	v_cvt_pk_bf16_f32 v224, v246, v247
	v_cvt_pk_bf16_f32 v225, v248, v249
	ds_write_b128 v250, v[218:221] offset:19456
	ds_write_b128 v250, v[222:225] offset:58368
	s_waitcnt lgkmcnt(4)
	v_mfma_f32_16x16x32_bf16 v[92:95], v[88:91], v[146:149], v[0:3]
	s_nop 2
	s_waitcnt vmcnt(16)
	v_lshlrev_b32_e32 v242, 16, v230
	v_and_b32_e32 v243, 0xffff0000, v230
	v_lshlrev_b32_e32 v244, 16, v231
	v_and_b32_e32 v245, 0xffff0000, v231
	v_lshlrev_b32_e32 v246, 16, v232
	v_and_b32_e32 v247, 0xffff0000, v232
	v_lshlrev_b32_e32 v248, 16, v233
	v_and_b32_e32 v249, 0xffff0000, v233
	v_mul_f32_e32 v242, v106, v242
	v_mul_f32_e32 v243, v107, v243
	v_mul_f32_e32 v244, v106, v244
	v_mul_f32_e32 v245, v107, v245
	v_mul_f32_e32 v246, v106, v246
	v_mul_f32_e32 v247, v107, v247
	v_mul_f32_e32 v248, v106, v248
	v_mul_f32_e32 v249, v107, v249
	v_cvt_pk_bf16_f32 v230, v242, v243
	v_cvt_pk_bf16_f32 v231, v244, v245
	v_cvt_pk_bf16_f32 v232, v246, v247
	v_cvt_pk_bf16_f32 v233, v248, v249
	ds_write_b128 v250, v[226:229] offset:29184
	ds_write_b128 v119, v[230:233] offset:58368
	s_waitcnt lgkmcnt(2)
	v_mfma_f32_16x16x32_bf16 v[68:71], v[130:133], v[150:153], v[80:83]
	s_nop 2
	v_lshl_add_u64 v[80:81], v[110:111], 0, s[28:29]
	v_mfma_f32_16x16x32_bf16 v[88:91], v[88:91], v[150:153], v[64:67]
	v_mfma_f32_16x16x32_bf16 v[64:67], v[130:133], v[146:149], v[142:145]
	v_lshl_add_u64 v[130:131], v[80:81], 0, v[96:97]
	v_lshl_add_u64 v[132:133], v[80:81], 0, v[114:115]
	v_mfma_f32_16x16x32_bf16 v[72:75], v[134:137], v[146:149], v[154:157]
	v_cvt_pk_bf16_f32 v144, v68, v69
	s_nop 3
	v_cvt_pk_bf16_f32 v142, v64, v65
	v_cvt_pk_bf16_f32 v143, v66, v67
	v_mfma_f32_16x16x32_bf16 v[76:79], v[134:137], v[150:153], v[162:165]
	v_lshl_add_u64 v[134:135], v[80:81], 0, v[116:117]
	v_add_co_u32_e32 v136, vcc, s25, v130
	v_mfma_f32_16x16x32_bf16 v[80:83], v[138:141], v[146:149], v[166:169]
	s_nop 0
	v_addc_co_u32_e32 v137, vcc, 0, v131, vcc
	v_cvt_pk_bf16_f32 v145, v70, v71
	v_mfma_f32_16x16x32_bf16 v[84:87], v[138:141], v[150:153], v[84:87]
	v_cvt_pk_bf16_f32 v138, v92, v93
	v_cvt_pk_bf16_f32 v139, v94, v95
	v_cvt_pk_bf16_f32 v140, v88, v89
	v_cvt_pk_bf16_f32 v141, v90, v91
	v_cvt_pk_bf16_f32 v146, v72, v73
	v_cvt_pk_bf16_f32 v147, v74, v75
	v_cvt_pk_bf16_f32 v148, v76, v77
	v_cvt_pk_bf16_f32 v149, v78, v79
	v_cvt_pk_bf16_f32 v150, v80, v81
	v_cvt_pk_bf16_f32 v151, v82, v83
	v_cvt_pk_bf16_f32 v152, v84, v85
	v_cvt_pk_bf16_f32 v153, v86, v87
	global_store_dwordx2 v[130:131], v[138:139], off
	global_store_dwordx2 v[136:137], v[140:141], off
	global_store_dwordx2 v[130:131], v[142:143], off offset:512
	global_store_dwordx2 v[132:133], v[144:145], off
	global_store_dwordx2 v[130:131], v[146:147], off offset:1024
	global_store_dwordx2 v[136:137], v[148:149], off offset:1024
	global_store_dwordx2 v[130:131], v[150:151], off offset:1536
	global_store_dwordx2 v[134:135], v[152:153], off
	v_mul_f32_e32 v54, v98, v90
	v_mul_f32_e32 v55, v99, v91
	v_mul_f32_e32 v52, v108, v88
	v_mul_f32_e32 v53, v109, v89
	v_mul_f32_e32 v50, v98, v94
	v_mul_f32_e32 v51, v99, v95
	v_mul_f32_e32 v48, v108, v92
	v_mul_f32_e32 v49, v109, v93
	v_add_u32_e32 v155, v120, v124
	s_waitcnt lgkmcnt(0)
	s_barrier
	s_min_u32 s12, s26, 29
	s_add_i32 s30, s12, 1
	s_sub_i32 s12, 30, s12
	s_and_b64 s[28:29], s[2:3], exec
	s_cselect_b32 s12, s30, s12
	s_lshl_b32 s12, s12, 7
	s_add_i32 s12, s12, s16
	s_mulk_i32 s12, 0x1c00
	v_lshl_add_u64 v[234:235], v[112:113], 0, s[12:13]
	v_lshl_add_u64 v[236:237], v[234:235], 0, s[4:5]
	v_lshl_add_u64 v[238:239], v[234:235], 0, s[8:9]
	v_lshl_add_u64 v[252:253], v[234:235], 0, s[10:11]
	global_load_dwordx4 v[202:205], v[234:235], off offset:1024
	global_load_dwordx4 v[206:209], v[234:235], off offset:2048
	global_load_dwordx4 v[210:213], v[236:237], off offset:1024
	global_load_dwordx4 v[214:217], v[236:237], off offset:2048
	global_load_dwordx4 v[218:221], v[238:239], off offset:1024
	global_load_dwordx4 v[222:225], v[238:239], off offset:2048
	global_load_dwordx4 v[226:229], v[252:253], off offset:1024
	global_load_dwordx4 v[230:233], v[252:253], off offset:2048
	v_add_u32_e32 v156, v121, v124
	ds_read_b64_tr_b16 v[34:35], v155 offset:1216
	ds_read_b64_tr_b16 v[32:33], v155
	ds_read_b64_tr_b16 v[36:37], v155 offset:32
	ds_read_b64_tr_b16 v[40:41], v155 offset:64
	ds_read_b64_tr_b16 v[44:45], v155 offset:96
	ds_read_b64_tr_b16 v[58:59], v156 offset:40128
	ds_read_b64_tr_b16 v[56:57], v156 offset:38912
	ds_read_b64_tr_b16 v[38:39], v155 offset:1248
	ds_read_b64_tr_b16 v[42:43], v155 offset:1280
	ds_read_b64_tr_b16 v[46:47], v155 offset:1312
	ds_read_b64_tr_b16 v[62:63], v156 offset:40160
	ds_read_b64_tr_b16 v[60:61], v156 offset:38944
	v_mul_f32_e32 v66, v98, v66
	v_mul_f32_e32 v67, v99, v67
	v_mul_f32_e32 v64, v108, v64
	v_mul_f32_e32 v65, v109, v65
	v_mul_f32_e32 v70, v98, v70
	v_mul_f32_e32 v71, v99, v71
	v_mul_f32_e32 v68, v108, v68
	v_mul_f32_e32 v69, v109, v69
	s_waitcnt lgkmcnt(5)
	v_mfma_f32_16x16x32_bf16 v[48:51], v[32:35], v[56:59], v[48:51]
	s_nop 2
	s_waitcnt lgkmcnt(0)
	v_mfma_f32_16x16x32_bf16 v[32:35], v[32:35], v[60:63], v[52:55]
	s_nop 2
	v_mul_f32_e32 v54, v98, v74
	v_mul_f32_e32 v55, v99, v75
	v_mul_f32_e32 v52, v108, v72
	v_mul_f32_e32 v53, v109, v73
	v_mfma_f32_16x16x32_bf16 v[64:67], v[36:39], v[56:59], v[64:67]
	v_mul_f32_e64 v74, v98, v78
	v_mul_f32_e64 v75, v99, v79
	v_mul_f32_e32 v72, v108, v76
	v_mul_f32_e32 v73, v109, v77
	v_mul_f32_e32 v78, v98, v82
	v_mul_f32_e32 v79, v99, v83
	v_mfma_f32_16x16x32_bf16 v[36:39], v[36:39], v[60:63], v[68:71]
	v_mul_f32_e64 v76, v108, v80
	v_mul_f32_e64 v77, v109, v81
	s_nop 1
	v_mul_f32_e32 v70, v98, v86
	v_mul_f32_e32 v71, v99, v87
	v_mul_f32_e32 v68, v108, v84
	v_mul_f32_e32 v69, v109, v85
	v_mfma_f32_16x16x32_bf16 v[52:55], v[40:43], v[56:59], v[52:55]
	ds_read_b64_tr_b16 v[80:81], v155 offset:9728
	ds_read_b64_tr_b16 v[84:85], v155 offset:9760
	ds_read_b64_tr_b16 v[88:89], v155 offset:9792
	ds_read_b64_tr_b16 v[82:83], v155 offset:10944
	ds_read_b64_tr_b16 v[86:87], v155 offset:10976
	ds_read_b64_tr_b16 v[90:91], v155 offset:11008
	s_and_b64 s[28:29], s[2:3], exec
	v_mfma_f32_16x16x32_bf16 v[40:43], v[40:43], v[60:63], v[72:75]
	v_mfma_f32_16x16x32_bf16 v[56:59], v[44:47], v[56:59], v[76:79]
	s_nop 1
	ds_read_b64_tr_b16 v[72:73], v155 offset:9824
	ds_read_b64_tr_b16 v[76:77], v156 offset:48640
	ds_read_b64_tr_b16 v[78:79], v156 offset:49856
	v_mfma_f32_16x16x32_bf16 v[44:47], v[44:47], v[60:63], v[68:71]
	ds_read_b64_tr_b16 v[74:75], v155 offset:11040
	ds_read_b64_tr_b16 v[62:63], v156 offset:49888
	ds_read_b64_tr_b16 v[60:61], v156 offset:48672
	s_waitcnt lgkmcnt(3)
	v_mfma_f32_16x16x32_bf16 v[48:51], v[80:83], v[76:79], v[48:51]
	s_waitcnt lgkmcnt(0)
	v_mfma_f32_16x16x32_bf16 v[32:35], v[80:83], v[60:63], v[32:35]
	v_mfma_f32_16x16x32_bf16 v[64:67], v[84:87], v[76:79], v[64:67]
	v_mfma_f32_16x16x32_bf16 v[36:39], v[84:87], v[60:63], v[36:39]
	ds_read_b64_tr_b16 v[68:69], v155 offset:19456
	ds_read_b64_tr_b16 v[80:81], v155 offset:19488
	ds_read_b64_tr_b16 v[84:85], v155 offset:19520
	ds_read_b64_tr_b16 v[70:71], v155 offset:20672
	ds_read_b64_tr_b16 v[82:83], v155 offset:20704
	ds_read_b64_tr_b16 v[86:87], v155 offset:20736
	v_mfma_f32_16x16x32_bf16 v[52:55], v[88:91], v[76:79], v[52:55]
	v_mfma_f32_16x16x32_bf16 v[40:43], v[88:91], v[60:63], v[40:43]
	v_mfma_f32_16x16x32_bf16 v[56:59], v[72:75], v[76:79], v[56:59]
	ds_read_b64_tr_b16 v[76:77], v155 offset:19552
	ds_read_b64_tr_b16 v[88:89], v156 offset:58368
	ds_read_b64_tr_b16 v[90:91], v156 offset:59584
	v_mfma_f32_16x16x32_bf16 v[44:47], v[72:75], v[60:63], v[44:47]
	ds_read_b64_tr_b16 v[78:79], v155 offset:20768
	ds_read_b64_tr_b16 v[62:63], v156 offset:59616
	ds_read_b64_tr_b16 v[60:61], v156 offset:58400
	s_waitcnt vmcnt(22)
	v_lshlrev_b32_e32 v242, 16, v174
	v_and_b32_e32 v243, 0xffff0000, v174
	v_lshlrev_b32_e32 v244, 16, v175
	v_and_b32_e32 v245, 0xffff0000, v175
	v_lshlrev_b32_e32 v246, 16, v176
	v_and_b32_e32 v247, 0xffff0000, v176
	v_lshlrev_b32_e32 v248, 16, v177
	v_and_b32_e32 v249, 0xffff0000, v177
	v_mul_f32_e32 v242, v100, v242
	v_mul_f32_e32 v243, v101, v243
	v_mul_f32_e32 v244, v100, v244
	v_mul_f32_e32 v245, v101, v245
	v_mul_f32_e32 v246, v100, v246
	v_mul_f32_e32 v247, v101, v247
	v_mul_f32_e32 v248, v100, v248
	v_mul_f32_e32 v249, v101, v249
	v_cvt_pk_bf16_f32 v174, v242, v243
	v_cvt_pk_bf16_f32 v175, v244, v245
	v_cvt_pk_bf16_f32 v176, v246, v247
	v_cvt_pk_bf16_f32 v177, v248, v249
	ds_write_b128 v125, v[170:173]
	ds_write_b128 v126, v[174:177]
	s_waitcnt lgkmcnt(5)
	v_mfma_f32_16x16x32_bf16 v[72:75], v[80:83], v[88:91], v[64:67]
	s_waitcnt vmcnt(20)
	v_lshlrev_b32_e32 v242, 16, v182
	v_and_b32_e32 v243, 0xffff0000, v182
	v_lshlrev_b32_e32 v244, 16, v183
	v_and_b32_e32 v245, 0xffff0000, v183
	v_lshlrev_b32_e32 v246, 16, v184
	v_and_b32_e32 v247, 0xffff0000, v184
	v_lshlrev_b32_e32 v248, 16, v185
	v_and_b32_e32 v249, 0xffff0000, v185
	v_mul_f32_e32 v242, v102, v242
	v_mul_f32_e32 v243, v103, v243
	v_mul_f32_e32 v244, v102, v244
	v_mul_f32_e32 v245, v103, v245
	v_mul_f32_e32 v246, v102, v246
	v_mul_f32_e32 v247, v103, v247
	v_mul_f32_e32 v248, v102, v248
	v_mul_f32_e32 v249, v103, v249
	v_cvt_pk_bf16_f32 v182, v242, v243
	v_cvt_pk_bf16_f32 v183, v244, v245
	v_cvt_pk_bf16_f32 v184, v246, v247
	v_cvt_pk_bf16_f32 v185, v248, v249
	ds_write_b128 v125, v[178:181] offset:9728
	ds_write_b128 v126, v[182:185] offset:9728
	s_waitcnt lgkmcnt(4)
	v_mfma_f32_16x16x32_bf16 v[80:83], v[80:83], v[60:63], v[36:39]
	s_nop 2
	ds_read_b64_tr_b16 v[36:37], v155 offset:29184
	ds_read_b64_tr_b16 v[38:39], v155 offset:30400
	ds_read_b64_tr_b16 v[132:133], v155 offset:30432
	ds_read_b64_tr_b16 v[130:131], v155 offset:29216
	ds_read_b64_tr_b16 v[138:139], v155 offset:29248
	ds_read_b64_tr_b16 v[142:143], v155 offset:29280
	ds_read_b64_tr_b16 v[140:141], v155 offset:30464
	ds_read_b64_tr_b16 v[144:145], v155 offset:30496
	ds_read_b64_tr_b16 v[148:149], v122 offset:40128
	ds_read_b64_tr_b16 v[146:147], v122 offset:38912
	ds_read_b64_tr_b16 v[152:153], v122 offset:40160
	ds_read_b64_tr_b16 v[150:151], v122 offset:38944
	v_mfma_f32_16x16x32_bf16 v[48:51], v[68:71], v[88:91], v[48:51]
	v_mfma_f32_16x16x32_bf16 v[68:71], v[68:71], v[60:63], v[32:35]
	v_mfma_f32_16x16x32_bf16 v[134:137], v[84:87], v[88:91], v[52:55]
	v_mfma_f32_16x16x32_bf16 v[84:87], v[84:87], v[60:63], v[40:43]
	s_nop 2
	v_mfma_f32_16x16x32_bf16 v[154:157], v[76:79], v[60:63], v[44:47]
	v_mfma_f32_16x16x32_bf16 v[88:91], v[76:79], v[88:91], v[56:59]
	s_cselect_b32 s12, s26, s24
	s_add_i32 s12, s12, s17
	s_lshl_b64 s[28:29], s[12:13], 15
	s_waitcnt vmcnt(18)
	v_lshlrev_b32_e32 v242, 16, v190
	v_and_b32_e32 v243, 0xffff0000, v190
	v_lshlrev_b32_e32 v244, 16, v191
	v_and_b32_e32 v245, 0xffff0000, v191
	v_lshlrev_b32_e32 v246, 16, v192
	v_and_b32_e32 v247, 0xffff0000, v192
	v_lshlrev_b32_e32 v248, 16, v193
	v_and_b32_e32 v249, 0xffff0000, v193
	v_mul_f32_e32 v242, v104, v242
	v_mul_f32_e32 v243, v105, v243
	v_mul_f32_e32 v244, v104, v244
	v_mul_f32_e32 v245, v105, v245
	v_mul_f32_e32 v246, v104, v246
	v_mul_f32_e32 v247, v105, v247
	v_mul_f32_e32 v248, v104, v248
	v_mul_f32_e32 v249, v105, v249
	v_cvt_pk_bf16_f32 v190, v242, v243
	v_cvt_pk_bf16_f32 v191, v244, v245
	v_cvt_pk_bf16_f32 v192, v246, v247
	v_cvt_pk_bf16_f32 v193, v248, v249
	ds_write_b128 v125, v[186:189] offset:19456
	ds_write_b128 v126, v[190:193] offset:19456
	s_waitcnt lgkmcnt(4)
	v_mfma_f32_16x16x32_bf16 v[92:95], v[36:39], v[146:149], v[48:51]
	s_waitcnt vmcnt(16)
	v_lshlrev_b32_e32 v242, 16, v198
	v_and_b32_e32 v243, 0xffff0000, v198
	v_lshlrev_b32_e32 v244, 16, v199
	v_and_b32_e32 v245, 0xffff0000, v199
	v_lshlrev_b32_e32 v246, 16, v200
	v_and_b32_e32 v247, 0xffff0000, v200
	v_lshlrev_b32_e32 v248, 16, v201
	v_and_b32_e32 v249, 0xffff0000, v201
	v_mul_f32_e32 v242, v106, v242
	v_mul_f32_e32 v243, v107, v243
	v_mul_f32_e32 v244, v106, v244
	v_mul_f32_e32 v245, v107, v245
	v_mul_f32_e32 v246, v106, v246
	v_mul_f32_e32 v247, v107, v247
	v_mul_f32_e32 v248, v106, v248
	v_mul_f32_e32 v249, v107, v249
	v_cvt_pk_bf16_f32 v198, v242, v243
	v_cvt_pk_bf16_f32 v199, v244, v245
	v_cvt_pk_bf16_f32 v200, v246, v247
	v_cvt_pk_bf16_f32 v201, v248, v249
	ds_write_b128 v125, v[194:197] offset:29184
	ds_write_b128 v126, v[198:201] offset:29184
	s_waitcnt lgkmcnt(2)
	v_mfma_f32_16x16x32_bf16 v[64:67], v[36:39], v[150:153], v[68:71]
	s_nop 0
	s_nop 0
	s_nop 0
	v_mfma_f32_16x16x32_bf16 v[68:71], v[130:133], v[146:149], v[72:75]
	v_mfma_f32_16x16x32_bf16 v[72:75], v[130:133], v[150:153], v[80:83]
	v_lshl_add_u64 v[130:131], v[110:111], 0, s[28:29]
	v_lshl_add_u64 v[132:133], v[130:131], 0, v[96:97]
	v_mfma_f32_16x16x32_bf16 v[76:79], v[138:141], v[146:149], v[134:137]
	v_mfma_f32_16x16x32_bf16 v[80:83], v[138:141], v[150:153], v[84:87]
	s_nop 1
	v_add_co_u32_e32 v136, vcc, s25, v132
	v_cvt_pk_bf16_f32 v138, v92, v93
	v_mfma_f32_16x16x32_bf16 v[84:87], v[142:145], v[146:149], v[88:91]
	v_cvt_pk_bf16_f32 v139, v94, v95
	v_lshl_add_u64 v[134:135], v[130:131], 0, v[114:115]
	v_lshl_add_u64 v[130:131], v[130:131], 0, v[116:117]
	v_mfma_f32_16x16x32_bf16 v[88:91], v[142:145], v[150:153], v[154:157]
	v_addc_co_u32_e32 v137, vcc, 0, v133, vcc
	v_cvt_pk_bf16_f32 v140, v64, v65
	v_cvt_pk_bf16_f32 v141, v66, v67
	v_cvt_pk_bf16_f32 v142, v68, v69
	v_cvt_pk_bf16_f32 v143, v70, v71
	v_cvt_pk_bf16_f32 v144, v72, v73
	v_cvt_pk_bf16_f32 v145, v74, v75
	v_cvt_pk_bf16_f32 v146, v76, v77
	v_cvt_pk_bf16_f32 v147, v78, v79
	v_cvt_pk_bf16_f32 v148, v80, v81
	v_cvt_pk_bf16_f32 v149, v82, v83
	v_cvt_pk_bf16_f32 v150, v84, v85
	v_cvt_pk_bf16_f32 v151, v86, v87
	v_cvt_pk_bf16_f32 v152, v88, v89
	v_cvt_pk_bf16_f32 v153, v90, v91
	global_store_dwordx2 v[132:133], v[138:139], off
	global_store_dwordx2 v[136:137], v[140:141], off
	global_store_dwordx2 v[132:133], v[142:143], off offset:512
	global_store_dwordx2 v[134:135], v[144:145], off
	global_store_dwordx2 v[132:133], v[146:147], off offset:1024
	global_store_dwordx2 v[136:137], v[148:149], off offset:1024
	global_store_dwordx2 v[132:133], v[150:151], off offset:1536
	global_store_dwordx2 v[130:131], v[152:153], off
	s_add_i32 s24, s24, -2
	s_and_b64 vcc, exec, s[14:15]
	s_mov_b32 s26, s27
	s_cbranch_vccnz .LBB0_503
	s_setprio 0
	s_waitcnt lgkmcnt(0)
	s_barrier
